# W_out too: residual base (h1 in d_out, cold) pulled toward L2/MALL during the K-loop, one wave per K-iteration; D2 prefetch setup made SCC-safe
# speedup vs baseline: 1.0044x; 1.0031x over previous
; #define SEAM(k) do { if ((k) + 1 < ph_hi) xcd_barrier(xbar); } while (0)
; template <class Epi, class Sched, bool ALIGN_EPI = false, bool SP2 = false>
; __device__ __forceinline__ void gemm_phase(PG8_LAS unsigned char* lds, const Gemm g, const Sched& S, const Epi& E) {
;     const int tid = threadIdx.x, wid = __builtin_amdgcn_readfirstlane(tid >> 6), lane = tid & 63, wr = wid >> 2, wc = wid & 3, fr = lane & 15, fq = lane >> 4;
;     const int K = g.K, nt = K / BK;
;     unsigned voffA[2], voffB[2];
; #pragma unroll
;     for (int i = 0; i < 2; ++i) { int R, C; stage_rc(tid * 16 + i * 8192, R, C); const int Rb = Epi::PERM ? ((R & ~31) + perm32(R & 31)) : R;
;         voffA[i] = (unsigned)(R * K + C) * 2u; voffB[i] = (unsigned)(Rb * K + C) * 2u; }
;     const size_t kstep = (size_t)(BK * 2);
;     const size_t hstep = (size_t)HALF * K * 2;
;     const size_t tstep = 2 * hstep;
;     const unsigned ldsw = (unsigned)wid * 1024u;
;     const int aoff = lds_byte(wr * 64 + fr, fq * 8), boff = lds_byte(wc * 32 + fr, fq * 8);
;     ...
;     Unit cur, nxt; int ui = 0;
;     if (!S.next(0, cur)) return;
; __global__ void __launch_bounds__(NTHREADS, 2) mega(Params P, int ph_lo, int ph_hi) {
;     ...
;     if (IN(10)) { pg8::Gemm g{(const bf16*)(ws + OFF_RA), (const bf16*)(ws + OFF_WOUT), MMAIN, DM, DM}; pg8::StaticOrder S; S.init(MMAIN, DM, G, (int)blockIdx.x);
;         pg8::EpiResid E{nullptr, (const bf16*)P.out, nullptr, nullptr, (bf16*)(ws + OFF_HB2), ss2, 1.0f}; pg8::gemm_phase<pg8::EpiResid, pg8::StaticOrder, true, true>(lds, g, S, E); SEAM(10); }
.LBB0_996:
	s_add_u32 s0, s86, 0x2b52400
	s_addc_u32 s1, s87, 0
	s_cmp_gt_i32 s88, 10
	s_cselect_b64 s[2:3], -1, 0
	s_cmp_lt_i32 s89, 11
	s_cselect_b64 s[4:5], -1, 0
	s_or_b64 s[2:3], s[2:3], s[4:5]
	s_and_b64 vcc, exec, s[2:3]
	s_cbranch_vccnz .LBB0_1093
	v_readfirstlane_b32 s101, v209
	v_lshrrev_b32_e32 v240, 1, v209
	v_and_b32_e32 v241, 1, v209
	v_lshlrev_b32_e32 v240, 11, v240
	v_lshl_add_u32 v240, v241, 8, v240
	s_lshr_b32 s101, s101, 6
	s_lshl_b32 s101, s101, 1
	s_min_u32 s101, s101, 12
	s_cmpk_lt_i32 s33, 0x100
	s_cselect_b64 s[2:3], -1, 0
	s_cmpk_gt_i32 s33, 0xff
	v_readfirstlane_b32 s12, v209
	s_cbranch_scc1 .LBB0_1000
	s_ashr_i32 s4, s33, 31
	s_lshr_b32 s4, s4, 29
	s_add_i32 s6, s33, s4
	s_and_b32 s4, s6, -8
	s_sub_i32 s7, s33, s4
	s_cmp_gt_i32 s7, -1
	s_cbranch_scc0 .LBB0_1036
	s_lshl_b32 s8, s7, 5
	s_cbranch_execz .LBB0_1037
	s_branch .LBB0_1038

; #define PG8_STAGE(bufoff, gbase, voff) do { _Pragma("unroll") for (int _i = 0; _i < 2; ++_i) \
;         __builtin_amdgcn_global_load_lds((const unsigned*)((const char*)(gbase) + (voff)[_i]), (PG8_LAS unsigned*)(lds + (bufoff) + ldsw + _i * 8192), 16, 0, 0); } while (0)
; #define PG8_LDA(dst, b, h) do { _Pragma("unroll") for (int m = 0; m < 4; ++m) _Pragma("unroll") for (int k = 0; k < 2; ++k) dst[m][k] = *(const PG8_LAS bf16x8*)(lds + PG8_SA(b, h) + aoff + m * 2048 + k * 1024); } while (0)
; #define PG8_LDB(dst, b, h) do { _Pragma("unroll") for (int n = 0; n < 2; ++n) _Pragma("unroll") for (int k = 0; k < 2; ++k) dst[n][k] = *(const PG8_LAS bf16x8*)(lds + PG8_SB(b, h) + boff + n * 2048 + k * 1024); } while (0)
; #define PG8_MMA(ai, bj, At, Bt) do { __builtin_amdgcn_s_setprio(1); _Pragma("unroll") for (int m = 0; m < 4; ++m) _Pragma("unroll") for (int n = 0; n < 2; ++n) _Pragma("unroll") for (int k = 0; k < 2; ++k) \
;         acc[ai][bj][m][n] = __builtin_amdgcn_mfma_f32_16x16x32_bf16(Bt[n][k], At[m][k], acc[ai][bj][m][n], 0, 0, 0); __builtin_amdgcn_s_setprio(0); } while (0)
; #define PG8_WAIT_V(n) asm volatile("s_waitcnt vmcnt(" #n ")" ::: "memory")
; #define PG8_WAIT_L(n) asm volatile("s_waitcnt lgkmcnt(" #n ")" ::: "memory")
; #define PG8_BAR __builtin_amdgcn_s_barrier()
; #define PG8_SCHED __builtin_amdgcn_sched_barrier(0)
; template <class Epi, class Sched, bool ALIGN_EPI = false, bool SP2 = false>
; __device__ __forceinline__ void gemm_phase(PG8_LAS unsigned char* lds, const Gemm g, const Sched& S, const Epi& E) {
;     ...
;             PG8_LDB(B0, 0, 0); PG8_LDB(B1, 0, 1); PG8_SCHED; PG8_LDA(At, 0, 0); PG8_STAGE(PG8_SA(1, 1), a1 + hstep, voffA);
;             PG8_WAIT_V(8); PG8_WAIT_L(0); PG8_BAR; PG8_MMA(0, 0, At, B0); PG8_MMA(0, 1, At, B1); PG8_BAR; PG8_SCHED;
;             PG8_LDA(At, 0, 1); PG8_STAGE(PG8_SB(0, 0), b2, voffB); PG8_STAGE(PG8_SB(0, 1), b2 + hstep, voffB); PG8_STAGE(PG8_SA(0, 0), a2, voffA);
;             PG8_WAIT_V(8); PG8_WAIT_L(0); PG8_BAR; PG8_MMA(1, 0, At, B0); PG8_MMA(1, 1, At, B1); PG8_BAR; PG8_SCHED;
.LBB0_1013:
	ds_read_b128 v[144:147], v151
	ds_read_b128 v[156:159], v151 offset:1024
	ds_read_b128 v[160:163], v151 offset:2048
	ds_read_b128 v[164:167], v151 offset:3072
	ds_read_b128 v[168:171], v152
	ds_read_b128 v[172:175], v152 offset:1024
	ds_read_b128 v[176:179], v152 offset:2048
	ds_read_b128 v[180:183], v152 offset:3072
	s_add_u32 s28, s26, 0xfffc0080
	s_addc_u32 s29, s27, -1
	s_cmp_eq_u32 s53, 12
	s_cselect_b32 s31, s17, s29
	s_cselect_b32 s30, s23, s28
	s_cselect_b32 s29, s15, s52
	s_cselect_b32 s28, s50, s51
	v_lshl_add_u64 v[218:219], s[26:27], 0, v[136:137]
	s_add_i32 m0, s25, 0xc000
	ds_read_b128 v[184:187], v153
	ds_read_b128 v[188:191], v153 offset:1024
	ds_read_b128 v[192:195], v153 offset:2048
	ds_read_b128 v[196:199], v153 offset:3072
	ds_read_b128 v[200:203], v153 offset:4096
	ds_read_b128 v[204:207], v153 offset:5120
	ds_read_b128 v[210:213], v153 offset:6144
	ds_read_b128 v[214:217], v153 offset:7168
	global_load_lds_dwordx4 v[218:219], off
	v_lshl_add_u64 v[218:219], s[26:27], 0, v[138:139]
	s_add_i32 m0, s25, 0xe000
	s_nop 0
	global_load_lds_dwordx4 v[218:219], off
	s_waitcnt vmcnt(8)
	s_waitcnt lgkmcnt(0)
	s_barrier
	s_cmp_eq_u32 s53, s101
	s_cbranch_scc0 .Lmy_pf10_skip
	s_lshl_b32 s98, s22, 19
	s_lshl_b32 s99, s24, 9
	s_add_i32 s98, s98, s99
	v_add_u32_e32 v241, s98, v240
	global_load_dword v242, v241, s[84:85]
	global_load_dword v242, v241, s[84:85] offset:128
.Lmy_pf10_skip:
	s_setprio 1
	s_waitcnt lgkmcnt(0)
	v_mfma_f32_16x16x32_bf16 v[124:127], v[144:147], v[184:187], v[124:127]
	v_mfma_f32_16x16x32_bf16 v[120:123], v[160:163], v[184:187], v[120:123]
	v_mfma_f32_16x16x32_bf16 v[108:111], v[144:147], v[192:195], v[108:111]
	v_mfma_f32_16x16x32_bf16 v[104:107], v[160:163], v[192:195], v[104:107]
	v_mfma_f32_16x16x32_bf16 v[92:95], v[144:147], v[200:203], v[92:95]
	v_mfma_f32_16x16x32_bf16 v[88:91], v[160:163], v[200:203], v[88:91]
	v_mfma_f32_16x16x32_bf16 v[76:79], v[144:147], v[210:213], v[76:79]
	v_mfma_f32_16x16x32_bf16 v[72:75], v[160:163], v[210:213], v[72:75]
	v_mfma_f32_16x16x32_bf16 v[124:127], v[156:159], v[188:191], v[124:127]
	v_mfma_f32_16x16x32_bf16 v[120:123], v[164:167], v[188:191], v[120:123]
	v_mfma_f32_16x16x32_bf16 v[108:111], v[156:159], v[196:199], v[108:111]
	v_mfma_f32_16x16x32_bf16 v[104:107], v[164:167], v[196:199], v[104:107]
	v_mfma_f32_16x16x32_bf16 v[92:95], v[156:159], v[204:207], v[92:95]
	v_mfma_f32_16x16x32_bf16 v[88:91], v[164:167], v[204:207], v[88:91]
	v_mfma_f32_16x16x32_bf16 v[76:79], v[156:159], v[214:217], v[76:79]
	v_mfma_f32_16x16x32_bf16 v[72:75], v[164:167], v[214:217], v[72:75]
	s_setprio 0
	s_setprio 1
	v_mfma_f32_16x16x32_bf16 v[116:119], v[168:171], v[184:187], v[116:119]
	v_mfma_f32_16x16x32_bf16 v[112:115], v[176:179], v[184:187], v[112:115]
	v_mfma_f32_16x16x32_bf16 v[100:103], v[168:171], v[192:195], v[100:103]
	v_mfma_f32_16x16x32_bf16 v[96:99], v[176:179], v[192:195], v[96:99]
	v_mfma_f32_16x16x32_bf16 v[84:87], v[168:171], v[200:203], v[84:87]
	v_mfma_f32_16x16x32_bf16 v[80:83], v[176:179], v[200:203], v[80:83]
	v_mfma_f32_16x16x32_bf16 v[68:71], v[168:171], v[210:213], v[68:71]
	v_mfma_f32_16x16x32_bf16 v[64:67], v[176:179], v[210:213], v[64:67]
	v_mfma_f32_16x16x32_bf16 v[116:119], v[172:175], v[188:191], v[116:119]
	v_mfma_f32_16x16x32_bf16 v[112:115], v[180:183], v[188:191], v[112:115]
	v_mfma_f32_16x16x32_bf16 v[100:103], v[172:175], v[196:199], v[100:103]
	v_mfma_f32_16x16x32_bf16 v[96:99], v[180:183], v[196:199], v[96:99]
	v_mfma_f32_16x16x32_bf16 v[84:87], v[172:175], v[204:207], v[84:87]
	v_mfma_f32_16x16x32_bf16 v[80:83], v[180:183], v[204:207], v[80:83]
	v_mfma_f32_16x16x32_bf16 v[68:71], v[172:175], v[214:217], v[68:71]
	v_mfma_f32_16x16x32_bf16 v[64:67], v[180:183], v[214:217], v[64:67]
	s_setprio 0
	s_barrier
	s_add_i32 s54, s48, s38
	v_lshl_add_u64 v[218:219], s[28:29], 0, v[130:131]
	s_mov_b32 m0, s54
	ds_read_b128 v[184:187], v153 offset:16384
	ds_read_b128 v[188:191], v153 offset:17408
	ds_read_b128 v[192:195], v153 offset:18432
	ds_read_b128 v[196:199], v153 offset:19456
	ds_read_b128 v[200:203], v153 offset:20480
	ds_read_b128 v[204:207], v153 offset:21504
	ds_read_b128 v[210:213], v153 offset:22528
	ds_read_b128 v[214:217], v153 offset:23552
	global_load_lds_dwordx4 v[218:219], off
	s_add_i32 m0, s54, 0x2000
	s_add_u32 s54, s28, 0x40000
	v_lshl_add_u64 v[220:221], s[28:29], 0, v[134:135]
	s_addc_u32 s55, s29, 0
	s_add_i32 s56, s49, s38
	global_load_lds_dwordx4 v[220:221], off
	v_lshl_add_u64 v[222:223], s[54:55], 0, v[130:131]
	s_mov_b32 m0, s56
	v_lshl_add_u64 v[224:225], s[30:31], 0, v[132:133]
	global_load_lds_dwordx4 v[222:223], off
	v_lshl_add_u64 v[222:223], s[54:55], 0, v[134:135]
	s_add_i32 m0, s56, 0x2000
	s_nop 0
	global_load_lds_dwordx4 v[222:223], off
	v_lshl_add_u64 v[222:223], s[30:31], 0, v[128:129]
	s_mov_b32 m0, s25
	s_nop 0
	global_load_lds_dwordx4 v[222:223], off
	s_mov_b32 m0, s39
	s_nop 0
	global_load_lds_dwordx4 v[224:225], off
	s_waitcnt vmcnt(8)
	s_waitcnt lgkmcnt(0)
	s_barrier
; #define PG8_STAGE(bufoff, gbase, voff) do { _Pragma("unroll") for (int _i = 0; _i < 2; ++_i) \
;         __builtin_amdgcn_global_load_lds((const unsigned*)((const char*)(gbase) + (voff)[_i]), (PG8_LAS unsigned*)(lds + (bufoff) + ldsw + _i * 8192), 16, 0, 0); } while (0)
; #define PG8_LDA(dst, b, h) do { _Pragma("unroll") for (int m = 0; m < 4; ++m) _Pragma("unroll") for (int k = 0; k < 2; ++k) dst[m][k] = *(const PG8_LAS bf16x8*)(lds + PG8_SA(b, h) + aoff + m * 2048 + k * 1024); } while (0)
; #define PG8_LDB(dst, b, h) do { _Pragma("unroll") for (int n = 0; n < 2; ++n) _Pragma("unroll") for (int k = 0; k < 2; ++k) dst[n][k] = *(const PG8_LAS bf16x8*)(lds + PG8_SB(b, h) + boff + n * 2048 + k * 1024); } while (0)
; #define PG8_MMA(ai, bj, At, Bt) do { __builtin_amdgcn_s_setprio(1); _Pragma("unroll") for (int m = 0; m < 4; ++m) _Pragma("unroll") for (int n = 0; n < 2; ++n) _Pragma("unroll") for (int k = 0; k < 2; ++k) \
;         acc[ai][bj][m][n] = __builtin_amdgcn_mfma_f32_16x16x32_bf16(Bt[n][k], At[m][k], acc[ai][bj][m][n], 0, 0, 0); __builtin_amdgcn_s_setprio(0); } while (0)
; #define PG8_WAIT_V(n) asm volatile("s_waitcnt vmcnt(" #n ")" ::: "memory")
; #define PG8_WAIT_L(n) asm volatile("s_waitcnt lgkmcnt(" #n ")" ::: "memory")
; #define PG8_BAR __builtin_amdgcn_s_barrier()
; #define PG8_SCHED __builtin_amdgcn_sched_barrier(0)
; template <class Epi, class Sched, bool ALIGN_EPI = false, bool SP2 = false>
; __device__ __forceinline__ void gemm_phase(PG8_LAS unsigned char* lds, const Gemm g, const Sched& S, const Epi& E) {
;     ...
;             PG8_WAIT_V(8); PG8_WAIT_L(0); PG8_BAR; PG8_MMA(1, 0, At, B0); PG8_MMA(1, 1, At, B1); PG8_BAR; PG8_SCHED;
;             PG8_LDB(B0, 1, 0); PG8_LDB(B1, 1, 1); PG8_SCHED; PG8_LDA(At, 1, 0); PG8_STAGE(PG8_SA(0, 1), a2 + hstep, voffA);
;             PG8_WAIT_V(8); PG8_WAIT_L(0); PG8_BAR; PG8_MMA(0, 0, At, B0); PG8_MMA(0, 1, At, B1); PG8_BAR; PG8_SCHED;
	s_setprio 1
	s_waitcnt lgkmcnt(0)
	v_mfma_f32_16x16x32_bf16 v[60:63], v[144:147], v[184:187], v[60:63]
	v_mfma_f32_16x16x32_bf16 v[56:59], v[160:163], v[184:187], v[56:59]
	v_mfma_f32_16x16x32_bf16 v[44:47], v[144:147], v[192:195], v[44:47]
	v_mfma_f32_16x16x32_bf16 v[40:43], v[160:163], v[192:195], v[40:43]
	v_mfma_f32_16x16x32_bf16 v[28:31], v[144:147], v[200:203], v[28:31]
	v_mfma_f32_16x16x32_bf16 v[24:27], v[160:163], v[200:203], v[24:27]
	v_mfma_f32_16x16x32_bf16 v[12:15], v[144:147], v[210:213], v[12:15]
	v_mfma_f32_16x16x32_bf16 v[8:11], v[160:163], v[210:213], v[8:11]
	v_mfma_f32_16x16x32_bf16 v[60:63], v[156:159], v[188:191], v[60:63]
	v_mfma_f32_16x16x32_bf16 v[56:59], v[164:167], v[188:191], v[56:59]
	v_mfma_f32_16x16x32_bf16 v[44:47], v[156:159], v[196:199], v[44:47]
	v_mfma_f32_16x16x32_bf16 v[40:43], v[164:167], v[196:199], v[40:43]
	v_mfma_f32_16x16x32_bf16 v[28:31], v[156:159], v[204:207], v[28:31]
	v_mfma_f32_16x16x32_bf16 v[24:27], v[164:167], v[204:207], v[24:27]
	v_mfma_f32_16x16x32_bf16 v[12:15], v[156:159], v[214:217], v[12:15]
	v_mfma_f32_16x16x32_bf16 v[8:11], v[164:167], v[214:217], v[8:11]
	s_setprio 0
	s_setprio 1
	v_mfma_f32_16x16x32_bf16 v[52:55], v[168:171], v[184:187], v[52:55]
	v_mfma_f32_16x16x32_bf16 v[48:51], v[176:179], v[184:187], v[48:51]
	v_mfma_f32_16x16x32_bf16 v[36:39], v[168:171], v[192:195], v[36:39]
	v_mfma_f32_16x16x32_bf16 v[32:35], v[176:179], v[192:195], v[32:35]
	v_mfma_f32_16x16x32_bf16 v[20:23], v[168:171], v[200:203], v[20:23]
	v_mfma_f32_16x16x32_bf16 v[16:19], v[176:179], v[200:203], v[16:19]
	v_mfma_f32_16x16x32_bf16 v[4:7], v[168:171], v[210:213], v[4:7]
	v_mfma_f32_16x16x32_bf16 v[0:3], v[176:179], v[210:213], v[0:3]
	v_mfma_f32_16x16x32_bf16 v[52:55], v[172:175], v[188:191], v[52:55]
	v_mfma_f32_16x16x32_bf16 v[48:51], v[180:183], v[188:191], v[48:51]
	v_mfma_f32_16x16x32_bf16 v[36:39], v[172:175], v[196:199], v[36:39]
	v_mfma_f32_16x16x32_bf16 v[32:35], v[180:183], v[196:199], v[32:35]
	v_mfma_f32_16x16x32_bf16 v[20:23], v[172:175], v[204:207], v[20:23]
	v_mfma_f32_16x16x32_bf16 v[16:19], v[180:183], v[204:207], v[16:19]
	v_mfma_f32_16x16x32_bf16 v[4:7], v[172:175], v[214:217], v[4:7]
	v_mfma_f32_16x16x32_bf16 v[0:3], v[180:183], v[214:217], v[0:3]
	s_setprio 0
	s_barrier
	s_add_i32 s54, 0, 0x18000
	v_add_u32_e32 v155, s54, v149
	s_add_i32 s55, 0, 0x1c000
	ds_read_b128 v[144:147], v155
	ds_read_b128 v[156:159], v155 offset:1024
	ds_read_b128 v[160:163], v155 offset:2048
	ds_read_b128 v[164:167], v155 offset:3072
	v_add_u32_e32 v155, s55, v149
	ds_read_b128 v[168:171], v155
	ds_read_b128 v[172:175], v155 offset:1024
	ds_read_b128 v[176:179], v155 offset:2048
	ds_read_b128 v[180:183], v155 offset:3072
	s_add_u32 s30, s30, 0x40000
	s_addc_u32 s31, s31, 0
	s_mov_b32 m0, s40
	v_lshl_add_u64 v[226:227], s[30:31], 0, v[128:129]
	ds_read_b128 v[184:187], v153 offset:32768
	ds_read_b128 v[188:191], v153 offset:33792
	ds_read_b128 v[192:195], v153 offset:34816
	ds_read_b128 v[196:199], v153 offset:35840
	ds_read_b128 v[200:203], v153 offset:36864
	ds_read_b128 v[204:207], v153 offset:37888
	ds_read_b128 v[210:213], v153 offset:38912
	ds_read_b128 v[214:217], v153 offset:39936
	global_load_lds_dwordx4 v[226:227], off
	v_lshl_add_u64 v[226:227], s[30:31], 0, v[132:133]
	s_mov_b32 m0, s41
	s_nop 0
	global_load_lds_dwordx4 v[226:227], off
	s_waitcnt vmcnt(8)
	s_waitcnt lgkmcnt(0)
	s_barrier
	s_setprio 1
	s_waitcnt lgkmcnt(0)
	v_mfma_f32_16x16x32_bf16 v[124:127], v[144:147], v[184:187], v[124:127]
	v_mfma_f32_16x16x32_bf16 v[120:123], v[160:163], v[184:187], v[120:123]
	v_mfma_f32_16x16x32_bf16 v[108:111], v[144:147], v[192:195], v[108:111]
	v_mfma_f32_16x16x32_bf16 v[104:107], v[160:163], v[192:195], v[104:107]
	v_mfma_f32_16x16x32_bf16 v[92:95], v[144:147], v[200:203], v[92:95]
	v_mfma_f32_16x16x32_bf16 v[88:91], v[160:163], v[200:203], v[88:91]
	v_mfma_f32_16x16x32_bf16 v[76:79], v[144:147], v[210:213], v[76:79]
	v_mfma_f32_16x16x32_bf16 v[72:75], v[160:163], v[210:213], v[72:75]
	v_mfma_f32_16x16x32_bf16 v[124:127], v[156:159], v[188:191], v[124:127]
	v_mfma_f32_16x16x32_bf16 v[120:123], v[164:167], v[188:191], v[120:123]
	v_mfma_f32_16x16x32_bf16 v[108:111], v[156:159], v[196:199], v[108:111]
	v_mfma_f32_16x16x32_bf16 v[104:107], v[164:167], v[196:199], v[104:107]
	v_mfma_f32_16x16x32_bf16 v[92:95], v[156:159], v[204:207], v[92:95]
	v_mfma_f32_16x16x32_bf16 v[88:91], v[164:167], v[204:207], v[88:91]
	v_mfma_f32_16x16x32_bf16 v[76:79], v[156:159], v[214:217], v[76:79]
	v_mfma_f32_16x16x32_bf16 v[72:75], v[164:167], v[214:217], v[72:75]
	s_setprio 0
	s_setprio 1
	v_mfma_f32_16x16x32_bf16 v[116:119], v[168:171], v[184:187], v[116:119]
	v_mfma_f32_16x16x32_bf16 v[112:115], v[176:179], v[184:187], v[112:115]
	v_mfma_f32_16x16x32_bf16 v[100:103], v[168:171], v[192:195], v[100:103]
	v_mfma_f32_16x16x32_bf16 v[96:99], v[176:179], v[192:195], v[96:99]
	v_mfma_f32_16x16x32_bf16 v[84:87], v[168:171], v[200:203], v[84:87]
	v_mfma_f32_16x16x32_bf16 v[80:83], v[176:179], v[200:203], v[80:83]
	v_mfma_f32_16x16x32_bf16 v[68:71], v[168:171], v[210:213], v[68:71]
	v_mfma_f32_16x16x32_bf16 v[64:67], v[176:179], v[210:213], v[64:67]
	v_mfma_f32_16x16x32_bf16 v[116:119], v[172:175], v[188:191], v[116:119]
	v_mfma_f32_16x16x32_bf16 v[112:115], v[180:183], v[188:191], v[112:115]
	v_mfma_f32_16x16x32_bf16 v[100:103], v[172:175], v[196:199], v[100:103]
	v_mfma_f32_16x16x32_bf16 v[96:99], v[180:183], v[196:199], v[96:99]
	v_mfma_f32_16x16x32_bf16 v[84:87], v[172:175], v[204:207], v[84:87]
	v_mfma_f32_16x16x32_bf16 v[80:83], v[180:183], v[204:207], v[80:83]
	v_mfma_f32_16x16x32_bf16 v[68:71], v[172:175], v[214:217], v[68:71]
	v_mfma_f32_16x16x32_bf16 v[64:67], v[180:183], v[214:217], v[64:67]
	s_setprio 0
	s_barrier
; #define PG8_STAGE(bufoff, gbase, voff) do { _Pragma("unroll") for (int _i = 0; _i < 2; ++_i) \
;         __builtin_amdgcn_global_load_lds((const unsigned*)((const char*)(gbase) + (voff)[_i]), (PG8_LAS unsigned*)(lds + (bufoff) + ldsw + _i * 8192), 16, 0, 0); } while (0)
; #define PG8_LDA(dst, b, h) do { _Pragma("unroll") for (int m = 0; m < 4; ++m) _Pragma("unroll") for (int k = 0; k < 2; ++k) dst[m][k] = *(const PG8_LAS bf16x8*)(lds + PG8_SA(b, h) + aoff + m * 2048 + k * 1024); } while (0)
; #define PG8_MMA(ai, bj, At, Bt) do { __builtin_amdgcn_s_setprio(1); _Pragma("unroll") for (int m = 0; m < 4; ++m) _Pragma("unroll") for (int n = 0; n < 2; ++n) _Pragma("unroll") for (int k = 0; k < 2; ++k) \
;         acc[ai][bj][m][n] = __builtin_amdgcn_mfma_f32_16x16x32_bf16(Bt[n][k], At[m][k], acc[ai][bj][m][n], 0, 0, 0); __builtin_amdgcn_s_setprio(0); } while (0)
; #define PG8_WAIT_V(n) asm volatile("s_waitcnt vmcnt(" #n ")" ::: "memory")
; #define PG8_WAIT_L(n) asm volatile("s_waitcnt lgkmcnt(" #n ")" ::: "memory")
; #define PG8_BAR __builtin_amdgcn_s_barrier()
; #define PG8_SCHED __builtin_amdgcn_sched_barrier(0)
; template <class Epi, class Sched, bool ALIGN_EPI = false, bool SP2 = false>
; __device__ __forceinline__ void gemm_phase(PG8_LAS unsigned char* lds, const Gemm g, const Sched& S, const Epi& E) {
;     ...
;             PG8_LDA(At, 1, 1); PG8_STAGE(PG8_SB(1, 0), b3, voffB); PG8_STAGE(PG8_SB(1, 1), b3 + hstep, voffB); PG8_STAGE(PG8_SA(1, 0), a3, voffA);
;             PG8_WAIT_V(8); PG8_WAIT_L(0); PG8_BAR; PG8_MMA(1, 0, At, B0); PG8_MMA(1, 1, At, B1); PG8_BAR; PG8_SCHED;
	s_add_i32 s30, s54, s38
	v_lshl_add_u64 v[218:219], v[218:219], 0, s[10:11]
	s_mov_b32 m0, s30
	ds_read_b128 v[184:187], v153 offset:49152
	ds_read_b128 v[188:191], v153 offset:50176
	ds_read_b128 v[192:195], v153 offset:51200
	ds_read_b128 v[196:199], v153 offset:52224
	ds_read_b128 v[200:203], v153 offset:53248
	ds_read_b128 v[204:207], v153 offset:54272
	ds_read_b128 v[210:213], v153 offset:55296
	ds_read_b128 v[214:217], v153 offset:56320
	global_load_lds_dwordx4 v[218:219], off
	s_add_i32 m0, s30, 0x2000
	s_add_u32 s28, s28, 0x40080
	v_lshl_add_u64 v[218:219], v[220:221], 0, s[10:11]
	s_addc_u32 s29, s29, 0
	s_add_i32 s30, s55, s38
	global_load_lds_dwordx4 v[218:219], off
	v_lshl_add_u64 v[218:219], s[28:29], 0, v[130:131]
	s_mov_b32 m0, s30
	s_nop 0
	global_load_lds_dwordx4 v[218:219], off
	v_lshl_add_u64 v[218:219], s[28:29], 0, v[134:135]
	s_add_i32 m0, s30, 0x2000
	s_nop 0
	global_load_lds_dwordx4 v[218:219], off
	v_lshl_add_u64 v[218:219], v[222:223], 0, s[10:11]
	s_mov_b32 m0, s43
	s_nop 0
	global_load_lds_dwordx4 v[218:219], off
	v_lshl_add_u64 v[218:219], v[224:225], 0, s[10:11]
	s_mov_b32 m0, s44
	s_nop 0
	global_load_lds_dwordx4 v[218:219], off
	s_waitcnt vmcnt(8)
	s_waitcnt lgkmcnt(0)
	s_barrier
	s_setprio 1
	s_waitcnt lgkmcnt(0)
	v_mfma_f32_16x16x32_bf16 v[60:63], v[144:147], v[184:187], v[60:63]
	v_mfma_f32_16x16x32_bf16 v[56:59], v[160:163], v[184:187], v[56:59]
	v_mfma_f32_16x16x32_bf16 v[44:47], v[144:147], v[192:195], v[44:47]
	v_mfma_f32_16x16x32_bf16 v[40:43], v[160:163], v[192:195], v[40:43]
	v_mfma_f32_16x16x32_bf16 v[28:31], v[144:147], v[200:203], v[28:31]
	v_mfma_f32_16x16x32_bf16 v[24:27], v[160:163], v[200:203], v[24:27]
	v_mfma_f32_16x16x32_bf16 v[12:15], v[144:147], v[210:213], v[12:15]
	v_mfma_f32_16x16x32_bf16 v[8:11], v[160:163], v[210:213], v[8:11]
	v_mfma_f32_16x16x32_bf16 v[60:63], v[156:159], v[188:191], v[60:63]
	v_mfma_f32_16x16x32_bf16 v[56:59], v[164:167], v[188:191], v[56:59]
	v_mfma_f32_16x16x32_bf16 v[44:47], v[156:159], v[196:199], v[44:47]
	v_mfma_f32_16x16x32_bf16 v[40:43], v[164:167], v[196:199], v[40:43]
	v_mfma_f32_16x16x32_bf16 v[28:31], v[156:159], v[204:207], v[28:31]
	v_mfma_f32_16x16x32_bf16 v[24:27], v[164:167], v[204:207], v[24:27]
	v_mfma_f32_16x16x32_bf16 v[12:15], v[156:159], v[214:217], v[12:15]
	v_mfma_f32_16x16x32_bf16 v[8:11], v[164:167], v[214:217], v[8:11]
	s_setprio 0
	s_setprio 1
	v_mfma_f32_16x16x32_bf16 v[52:55], v[168:171], v[184:187], v[52:55]
	v_mfma_f32_16x16x32_bf16 v[48:51], v[176:179], v[184:187], v[48:51]
	v_mfma_f32_16x16x32_bf16 v[36:39], v[168:171], v[192:195], v[36:39]
	v_mfma_f32_16x16x32_bf16 v[32:35], v[176:179], v[192:195], v[32:35]
	v_mfma_f32_16x16x32_bf16 v[20:23], v[168:171], v[200:203], v[20:23]
	v_mfma_f32_16x16x32_bf16 v[16:19], v[176:179], v[200:203], v[16:19]
	v_mfma_f32_16x16x32_bf16 v[4:7], v[168:171], v[210:213], v[4:7]
	v_mfma_f32_16x16x32_bf16 v[0:3], v[176:179], v[210:213], v[0:3]
	v_mfma_f32_16x16x32_bf16 v[52:55], v[172:175], v[188:191], v[52:55]
	v_mfma_f32_16x16x32_bf16 v[48:51], v[180:183], v[188:191], v[48:51]
	v_mfma_f32_16x16x32_bf16 v[36:39], v[172:175], v[196:199], v[36:39]
	v_mfma_f32_16x16x32_bf16 v[32:35], v[180:183], v[196:199], v[32:35]
	v_mfma_f32_16x16x32_bf16 v[20:23], v[172:175], v[204:207], v[20:23]
	v_mfma_f32_16x16x32_bf16 v[16:19], v[180:183], v[204:207], v[16:19]
	v_mfma_f32_16x16x32_bf16 v[4:7], v[172:175], v[214:217], v[4:7]
	v_mfma_f32_16x16x32_bf16 v[0:3], v[180:183], v[214:217], v[0:3]
	s_setprio 0
	s_barrier
	s_add_i32 s53, s53, 2
	s_add_u32 s26, s26, 0x100
	s_addc_u32 s27, s27, 0
	s_add_u32 s51, s51, 0x100
	s_addc_u32 s52, s52, 0
	s_cmp_gt_u32 s53, 13
	s_cbranch_scc0 .LBB0_1013
	s_and_b64 vcc, exec, s[12:13]
	s_cbranch_vccz .LBB0_1016
	s_barrier

; template <class Epi, class Sched, bool ALIGN_EPI = false, bool SP2 = false>
; __device__ __forceinline__ void gemm_phase(PG8_LAS unsigned char* lds, const Gemm g, const Sched& S, const Epi& E) {
;     const int tid = threadIdx.x, wid = __builtin_amdgcn_readfirstlane(tid >> 6), lane = tid & 63, wr = wid >> 2, wc = wid & 3, fr = lane & 15, fq = lane >> 4;
;     const int K = g.K, nt = K / BK;
;     unsigned voffA[2], voffB[2];
; #pragma unroll
;     for (int i = 0; i < 2; ++i) { int R, C; stage_rc(tid * 16 + i * 8192, R, C); const int Rb = Epi::PERM ? ((R & ~31) + perm32(R & 31)) : R;
;         voffA[i] = (unsigned)(R * K + C) * 2u; voffB[i] = (unsigned)(Rb * K + C) * 2u; }
;     const size_t kstep = (size_t)(BK * 2);
;     const size_t hstep = (size_t)HALF * K * 2;
;     const size_t tstep = 2 * hstep;
;     const unsigned ldsw = (unsigned)wid * 1024u;
;     const int aoff = lds_byte(wr * 64 + fr, fq * 8), boff = lds_byte(wc * 32 + fr, fq * 8);
;     ...
;     Unit cur, nxt; int ui = 0;
;     if (!S.next(0, cur)) return;
; __global__ void __launch_bounds__(NTHREADS, 2) mega(Params P, int ph_lo, int ph_hi) {
;     ...
;     if (IN(13)) { pg8::Gemm g{(const bf16*)(ws + OFF_ACT), (const bf16*)(ws + OFF_WD2), MMAIN, DM, DFF}; pg8::StaticOrder S; S.init(MMAIN, DM, G, (int)blockIdx.x);
;         pg8::EpiResid E{nullptr, (const bf16*)(ws + OFF_HB2), nullptr, P.out, nullptr, nullptr, 0.5f}; pg8::gemm_phase<pg8::EpiResid, pg8::StaticOrder, true, true>(lds, g, S, E); }
.LBB0_1168:
	s_cmp_gt_i32 s88, 13
	s_cselect_b64 s[0:1], -1, 0
	s_cmp_lt_i32 s89, 14
	s_cselect_b64 s[2:3], -1, 0
	s_or_b64 s[0:1], s[0:1], s[2:3]
	s_and_b64 vcc, exec, s[0:1]
	s_cbranch_vccnz .LBB0_1199
	v_readfirstlane_b32 s101, v209
	v_lshrrev_b32_e32 v240, 1, v209
	v_and_b32_e32 v241, 1, v209
	v_lshlrev_b32_e32 v240, 11, v240
	v_lshl_add_u32 v240, v241, 8, v240
	s_lshr_b32 s101, s101, 6
	s_lshl_b32 s101, s101, 1
	s_add_i32 s101, s101, 26
	s_cmpk_gt_i32 s33, 0xff
	v_readfirstlane_b32 s2, v209
	s_cbranch_scc1 .LBB0_1199
	s_ashr_i32 s22, s33, 31
	s_lshr_b32 s0, s22, 29
	s_add_i32 s5, s33, s0
	s_and_b32 s0, s5, -8
	s_sub_i32 s3, s33, s0
	s_cmp_gt_i32 s3, -1
	s_cbranch_scc0 .LBB0_1172
	s_lshl_b32 s4, s3, 5
	s_ashr_i32 s1, s5, 3
	s_cbranch_execz .LBB0_1173
	s_branch .LBB0_1174
